# v68 with the pmat unit loop software-pipelined across units: next unit's 16 q/k loads issued after this unit's staging barrier into spare v128-v191 (replaces the in-unit rolling pipeline)
# speedup vs baseline: 1.0017x; 1.0003x over previous
; #define GAS __attribute__((address_space(1)))
; #define LAS __attribute__((address_space(3)))
; __device__ __forceinline__ unsigned argw(const Frame& F, int w) { return ((const volatile LAS unsigned*)(F.lds + ARGS_OFF + F.zero))[w]; }
; __device__ __forceinline__ void pmat_phase(const Frame& F, const bf16_t* Q, const bf16_t* K, bf16_t* PB, int half) {
;     const int nseq = half ? NS : NP, nchunk = half ? LP_S / 128 : LP_P / 128;
;     const int nunits = nseq * nchunk * RH;
;     const int tid = F.tid, lane = tid & 63, wv = tid >> 6, l15 = lane & 15, quad = lane >> 4;
;     LAS unsigned char* const lg = F.lds;
;     LAS unsigned char* const bQown = lg + (16 * wv + l15) * PS + 16 * quad;
;     LAS unsigned char* const bK    = lg + 128 * PS + l15 * PS + 16 * quad;
;     const int srow = tid >> 5, scc = tid & 31;
;     for (int u = F.vcu; u < nunits; u += F.G) {
;         const int head = u & 7, sc = u >> 3;
;         const float lgf = __uint_as_float(__builtin_amdgcn_readfirstlane(argw(F, AW_LG2 + head))), lgb = __uint_as_float(__builtin_amdgcn_readfirstlane(argw(F, AW_LG2 + 8 + head)));
;         const size_t u0 = (size_t)sc * 128 * 2048 + head * 256; const unsigned lq = (unsigned)(srow * 2048 + scc * 8);
; #pragma unroll
;         for (int ii = 0; ii < 8; ++ii) { const u32x4 qv = *(const GAS u32x4*)(Q + u0 + (size_t)ii * 16 * 2048 + lq), kv = *(const GAS u32x4*)(K + u0 + (size_t)ii * 16 * 2048 + lq);
;             *(LAS u32x4*)(lg + (srow + 16 * ii) * PS + scc * 16) = qv; *(LAS u32x4*)(lg + 128 * PS + (srow + 16 * ii) * PS + scc * 16) = kv; }
;         __syncthreads();
;         bf16x8 Qf[8];
; #pragma unroll
;         for (int ks = 0; ks < 8; ++ks) Qf[ks] = *(const LAS bf16x8*)(bQown + 64 * ks);
;         bf16_t* pout = PB + (size_t)u * 16384; const unsigned lpo = (unsigned)((16 * wv + l15) * 128 + 4 * quad); const int i_abs = 16 * wv + l15;
; #pragma unroll
;         for (int jt = 0; jt < 8; ++jt) { f32x4 st = {0.f, 0.f, 0.f, 0.f};
; #pragma unroll
;             for (int ks = 0; ks < 8; ++ks) { const bf16x8 Kf = *(const LAS bf16x8*)(bK + 16 * jt * PS + 64 * ks); st = __builtin_amdgcn_mfma_f32_16x16x32_bf16(Kf, Qf[ks], st, 0, 0, 0); }
; #pragma unroll
;             for (int r = 0; r < 4; ++r) { const int jj = 16 * jt + 4 * quad + r;
;                 st[r] *= __builtin_amdgcn_exp2f(jj <= i_abs ? lgf * (float)(-jj - 1) : lgb * (float)(jj - 128)); }
.LBB0_912:
	v_readlane_b32 s0, v254, 3
	v_readlane_b32 s1, v254, 4
	s_cmp_ge_i32 s18, s0
	s_cselect_b64 s[0:1], -1, 0
	v_writelane_b32 v255, s0, 61
	s_nop 1
	v_writelane_b32 v255, s1, 62
	s_and_b64 s[0:1], s[0:1], s[22:23]
	s_andn2_b64 vcc, exec, s[0:1]
	s_cbranch_vccnz .LBB0_917
	s_mov_b32 s0, -1
	v_readlane_b32 s28, v255, 58
	v_mbcnt_lo_u32_b32 v0, s0, 0
	v_mbcnt_hi_u32_b32 v0, s0, v0
	v_readlane_b32 s0, v254, 5
	v_readlane_b32 s29, v255, 59
	s_and_b64 s[36:37], s[28:29], exec
	v_add_u32_e32 v1, s0, v0
	v_readlane_b32 s0, v254, 2
	s_mov_b32 s22, s0
	v_mov_b32_e32 v0, v193
	s_movk_i32 s13, 0x820
	v_add_u32_e32 v2, 0, v0
	v_add_u32_e32 v3, 0x23ba8, v2
	ds_read_b32 v3, v3
	v_add_u32_e32 v4, 0x23bac, v2
	v_add_u32_e32 v5, 0x23ba0, v2
	v_add_u32_e32 v2, 0x23ba4, v2
	ds_read_b32 v4, v4
	ds_read_b32 v6, v5
	ds_read_b32 v7, v2
	s_waitcnt lgkmcnt(0)
	v_readfirstlane_b32 s0, v3
	ds_read_b32 v3, v5
	ds_read_b32 v2, v2
	s_cselect_b32 s18, s13, 0x840
	v_readfirstlane_b32 s1, v4
	v_readfirstlane_b32 s34, v6
	v_readfirstlane_b32 s35, v7
	s_waitcnt lgkmcnt(0)
	v_readfirstlane_b32 s12, v3
	s_cmp_ge_i32 s22, s18
	v_readfirstlane_b32 s13, v2
	s_cbranch_scc1 .LBB0_917
	v_ashrrev_i32_e32 v8, 2, v1
	v_bfi_b32 v9, -16, v8, v1
	s_movk_i32 s15, 0x210
	v_and_b32_e32 v6, 15, v1
	v_bfe_u32 v7, v1, 4, 2
	v_mul_lo_u32 v2, v9, s15
	v_add_u32_e32 v10, 0, v2
	v_lshlrev_b32_e32 v11, 4, v7
	v_mul_u32_u24_e32 v2, 0x210, v6
	v_readlane_b32 s23, v255, 23
	v_ashrrev_i32_e32 v12, 5, v1
	v_and_b32_e32 v1, 31, v1
	v_add3_u32 v38, s23, v2, v11
	v_lshlrev_b32_e32 v2, 3, v1
	v_lshl_or_b32 v192, v12, 11, v2
	v_lshlrev_b64 v[2:3], 1, v[192:193]
	v_lshl_add_u64 v[4:5], s[34:35], 0, v[2:3]
	v_lshl_add_u64 v[2:3], s[0:1], 0, v[2:3]
	s_mov_b64 s[0:1], 0x4a900000
	v_lshlrev_b32_e32 v1, 4, v1
	s_mov_b64 s[34:35], 0x10800000
	v_lshl_add_u64 v[34:35], v[2:3], 0, s[0:1]
	v_add_u32_e32 v2, 0, v1
	v_add_u32_e32 v3, s23, v1
	v_lshlrev_b32_e32 v1, 2, v7
	v_lshl_add_u64 v[32:33], v[4:5], 0, s[34:35]
	v_not_b32_e32 v5, v1
	v_cvt_f32_i32_e32 v39, v5
	v_or_b32_e32 v5, 0xffffff80, v1
	v_cvt_f32_i32_e32 v40, v5
	v_or_b32_e32 v5, 0xffffff81, v1
	v_cvt_f32_i32_e32 v41, v5
	v_xor_b32_e32 v5, -2, v1
	v_cvt_f32_i32_e32 v42, v5
	v_or_b32_e32 v5, 2, v1
	v_cmp_gt_i32_e64 s[36:37], v5, v9
	v_xor_b32_e32 v5, -3, v1
	v_cvt_f32_i32_e32 v43, v5
	v_or_b32_e32 v5, 0xffffff82, v1
	v_cvt_f32_i32_e32 v44, v5
	v_or_b32_e32 v5, 3, v1
	v_cmp_gt_i32_e64 s[38:39], v5, v9
	v_xor_b32_e32 v5, -4, v1
	v_cvt_f32_i32_e32 v45, v5
	v_or_b32_e32 v5, 0xffffff83, v1
	v_cvt_f32_i32_e32 v46, v5
	v_or_b32_e32 v5, 16, v1
	v_cmp_gt_i32_e64 s[40:41], v5, v9
	v_xor_b32_e32 v5, 0xffffffef, v1
	v_cvt_f32_i32_e32 v47, v5
	v_or_b32_e32 v5, 0xffffff90, v1
	v_cvt_f32_i32_e32 v48, v5
	v_or_b32_e32 v5, 17, v1
	v_cmp_gt_i32_e64 s[42:43], v5, v9
	v_xor_b32_e32 v5, 0xffffffee, v1
	v_cvt_f32_i32_e32 v49, v5
	v_or_b32_e32 v5, 0xffffff91, v1
	v_cvt_f32_i32_e32 v50, v5
	v_or_b32_e32 v5, 18, v1
	v_cmp_gt_i32_e64 s[44:45], v5, v9
	v_xor_b32_e32 v5, 0xffffffed, v1
	v_cvt_f32_i32_e32 v51, v5
	v_or_b32_e32 v5, 0xffffff92, v1
	v_cvt_f32_i32_e32 v52, v5
	v_or_b32_e32 v5, 19, v1
	v_cmp_gt_i32_e64 s[46:47], v5, v9
	v_xor_b32_e32 v5, 0xffffffec, v1
	v_cvt_f32_i32_e32 v53, v5
	v_or_b32_e32 v5, 0xffffff93, v1
	v_cvt_f32_i32_e32 v54, v5
	v_or_b32_e32 v5, 32, v1
	v_cmp_gt_i32_e64 s[48:49], v5, v9
	v_xor_b32_e32 v5, 0xffffffdf, v1
	v_cvt_f32_i32_e32 v55, v5
	v_or_b32_e32 v5, 0xffffffa0, v1
	v_cvt_f32_i32_e32 v56, v5
	v_or_b32_e32 v5, 33, v1
	v_cmp_gt_i32_e64 s[50:51], v5, v9
	v_xor_b32_e32 v5, 0xffffffde, v1
	v_cvt_f32_i32_e32 v57, v5
	v_or_b32_e32 v5, 0xffffffa1, v1
	v_cvt_f32_i32_e32 v58, v5
	v_or_b32_e32 v5, 34, v1
	v_cmp_gt_i32_e64 s[52:53], v5, v9
	v_xor_b32_e32 v5, 0xffffffdd, v1
	v_cvt_f32_i32_e32 v59, v5
	v_or_b32_e32 v5, 0xffffffa2, v1
	v_cvt_f32_i32_e32 v60, v5
	v_or_b32_e32 v5, 35, v1
	v_cmp_gt_i32_e64 s[54:55], v5, v9
	v_xor_b32_e32 v5, 0xffffffdc, v1
	v_cvt_f32_i32_e32 v61, v5
	v_or_b32_e32 v5, 0xffffffa3, v1
	v_cvt_f32_i32_e32 v62, v5
	v_or_b32_e32 v5, 48, v1
	v_cmp_gt_i32_e64 s[56:57], v5, v9
	v_xor_b32_e32 v5, 0xffffffcf, v1
	v_cvt_f32_i32_e32 v63, v5
	v_or_b32_e32 v5, 0xffffffb0, v1
	s_waitcnt vmcnt(0)
	v_cvt_f32_i32_e32 v64, v5
	v_or_b32_e32 v5, 49, v1
	v_cmp_gt_i32_e64 s[58:59], v5, v9
	v_xor_b32_e32 v5, 0xffffffce, v1
	v_cvt_f32_i32_e32 v65, v5
	v_or_b32_e32 v5, 0xffffffb1, v1
	v_cvt_f32_i32_e32 v66, v5
	v_or_b32_e32 v5, 50, v1
	v_cmp_gt_i32_e64 s[60:61], v5, v9
	v_xor_b32_e32 v5, 0xffffffcd, v1
	v_cvt_f32_i32_e32 v67, v5
	v_or_b32_e32 v5, 0xffffffb2, v1
	v_cvt_f32_i32_e32 v68, v5
	v_or_b32_e32 v5, 51, v1
	v_cmp_gt_i32_e64 s[62:63], v5, v9
	v_xor_b32_e32 v5, 0xffffffcc, v1
	v_cvt_f32_i32_e32 v69, v5
	v_or_b32_e32 v5, 0xffffffb3, v1
	v_cvt_f32_i32_e32 v70, v5
	v_or_b32_e32 v5, 64, v1
	v_cmp_gt_i32_e64 s[64:65], v5, v9
	v_xor_b32_e32 v5, 0xffffffbf, v1
	v_cvt_f32_i32_e32 v71, v5
	v_or_b32_e32 v5, 0xffffffc0, v1
	v_cvt_f32_i32_e32 v72, v5
	v_or_b32_e32 v5, 0x41, v1
	v_cmp_gt_i32_e64 s[66:67], v5, v9
	v_xor_b32_e32 v5, 0xffffffbe, v1
	v_cvt_f32_i32_e32 v73, v5
	v_or_b32_e32 v5, 0xffffffc1, v1
	v_cvt_f32_i32_e32 v74, v5
	v_or_b32_e32 v5, 0x42, v1
	v_cmp_gt_i32_e64 s[68:69], v5, v9
	v_xor_b32_e32 v5, 0xffffffbd, v1
	v_cvt_f32_i32_e32 v75, v5
	v_or_b32_e32 v5, 0xffffffc2, v1
	v_cvt_f32_i32_e32 v76, v5
	v_or_b32_e32 v5, 0x43, v1
	v_cmp_gt_i32_e64 s[70:71], v5, v9
	v_xor_b32_e32 v5, 0xffffffbc, v1
	v_cvt_f32_i32_e32 v77, v5
	v_or_b32_e32 v5, 0xffffffc3, v1
	v_cvt_f32_i32_e32 v78, v5
	v_or_b32_e32 v5, 0x50, v1
	v_cmp_gt_i32_e64 s[72:73], v5, v9
	v_xor_b32_e32 v5, 0xffffffaf, v1
	v_cvt_f32_i32_e32 v79, v5
	v_or_b32_e32 v5, 0xffffffd0, v1
	v_cvt_f32_i32_e32 v80, v5
; #define GAS __attribute__((address_space(1)))
; #define LAS __attribute__((address_space(3)))
; __device__ __forceinline__ unsigned argw(const Frame& F, int w) { return ((const volatile LAS unsigned*)(F.lds + ARGS_OFF + F.zero))[w]; }
; __device__ __forceinline__ void pmat_phase(const Frame& F, const bf16_t* Q, const bf16_t* K, bf16_t* PB, int half) {
;     ...
;     for (int u = F.vcu; u < nunits; u += F.G) {
;         const int head = u & 7, sc = u >> 3;
;         const float lgf = __uint_as_float(__builtin_amdgcn_readfirstlane(argw(F, AW_LG2 + head))), lgb = __uint_as_float(__builtin_amdgcn_readfirstlane(argw(F, AW_LG2 + 8 + head)));
;         const size_t u0 = (size_t)sc * 128 * 2048 + head * 256; const unsigned lq = (unsigned)(srow * 2048 + scc * 8);
; #pragma unroll
;         for (int ii = 0; ii < 8; ++ii) { const u32x4 qv = *(const GAS u32x4*)(Q + u0 + (size_t)ii * 16 * 2048 + lq), kv = *(const GAS u32x4*)(K + u0 + (size_t)ii * 16 * 2048 + lq);
;             *(LAS u32x4*)(lg + (srow + 16 * ii) * PS + scc * 16) = qv; *(LAS u32x4*)(lg + 128 * PS + (srow + 16 * ii) * PS + scc * 16) = kv; }
	v_or_b32_e32 v5, 0x51, v1
	v_cmp_gt_i32_e64 s[74:75], v5, v9
	v_xor_b32_e32 v5, 0xffffffae, v1
	v_cvt_f32_i32_e32 v81, v5
	v_or_b32_e32 v5, 0xffffffd1, v1
	v_cvt_f32_i32_e32 v82, v5
	v_or_b32_e32 v5, 0x52, v1
	v_cmp_gt_i32_e64 s[76:77], v5, v9
	v_xor_b32_e32 v5, 0xffffffad, v1
	v_cvt_f32_i32_e32 v83, v5
	v_or_b32_e32 v5, 0xffffffd2, v1
	v_cvt_f32_i32_e32 v84, v5
	v_or_b32_e32 v5, 0x53, v1
	v_cmp_gt_i32_e64 s[78:79], v5, v9
	v_xor_b32_e32 v5, 0xffffffac, v1
	v_cvt_f32_i32_e32 v85, v5
	v_or_b32_e32 v5, 0xffffffd3, v1
	v_cvt_f32_i32_e32 v86, v5
	v_or_b32_e32 v5, 0x60, v1
	v_cmp_gt_i32_e64 s[80:81], v5, v9
	v_xor_b32_e32 v5, 0xffffff9f, v1
	v_cvt_f32_i32_e32 v87, v5
	v_or_b32_e32 v5, 0xffffffe0, v1
	v_cvt_f32_i32_e32 v88, v5
	v_or_b32_e32 v5, 0x61, v1
	v_cmp_gt_i32_e64 s[82:83], v5, v9
	v_xor_b32_e32 v5, 0xffffff9e, v1
	v_cvt_f32_i32_e32 v89, v5
	v_or_b32_e32 v5, 0xffffffe1, v1
	v_cvt_f32_i32_e32 v90, v5
	v_or_b32_e32 v5, 0x62, v1
	v_cmp_gt_i32_e64 s[84:85], v5, v9
	v_xor_b32_e32 v5, 0xffffff9d, v1
	v_cvt_f32_i32_e32 v91, v5
	v_or_b32_e32 v5, 0xffffffe2, v1
	v_cvt_f32_i32_e32 v92, v5
	v_or_b32_e32 v5, 0x63, v1
	v_cmp_gt_i32_e64 s[86:87], v5, v9
	v_xor_b32_e32 v5, 0xffffff9c, v1
	v_cvt_f32_i32_e32 v93, v5
	v_or_b32_e32 v5, 0xffffffe3, v1
	v_cvt_f32_i32_e32 v94, v5
	v_or_b32_e32 v5, 0x70, v1
	v_cmp_gt_i32_e64 s[88:89], v5, v9
	v_xor_b32_e32 v5, 0xffffff8f, v1
	v_cvt_f32_i32_e32 v95, v5
	v_or_b32_e32 v5, -16, v1
	v_cvt_f32_i32_e32 v96, v5
	v_or_b32_e32 v5, 0x71, v1
	v_cmp_gt_i32_e64 s[90:91], v5, v9
	v_xor_b32_e32 v5, 0xffffff8e, v1
	v_cvt_f32_i32_e32 v97, v5
	v_or_b32_e32 v5, -15, v1
	v_cvt_f32_i32_e32 v98, v5
	v_or_b32_e32 v5, 0x72, v1
	v_cmp_gt_i32_e64 s[92:93], v5, v9
	v_xor_b32_e32 v5, 0xffffff8d, v1
	v_cvt_f32_i32_e32 v99, v5
	v_or_b32_e32 v5, -14, v1
	v_cvt_f32_i32_e32 v100, v5
	v_or_b32_e32 v5, 0x73, v1
	s_add_i32 s23, 0, 0x23b00
	v_cmp_gt_i32_e64 s[94:95], v5, v9
	v_xor_b32_e32 v5, 0xffffff8c, v1
	v_add_u32_e32 v103, s23, v0
	s_ashr_i32 s23, s22, 31
	v_cvt_f32_i32_e32 v101, v5
	v_or_b32_e32 v5, -13, v1
	s_lshl_b64 vcc, s[22:23], 15
	v_lshlrev_b32_e32 v0, 7, v8
	v_cvt_f32_i32_e32 v102, v5
	v_and_b32_e32 v0, 0xfffff800, v0
	v_lshlrev_b32_e32 v5, 7, v6
	s_add_u32 s12, s12, vcc_lo
	v_or3_b32 v192, v0, v5, v1
	s_addc_u32 s13, s13, vcc_hi
	v_mul_lo_u32 v4, v12, s15
	v_cmp_gt_i32_e64 s[0:1], v1, v9
	v_cmp_lt_i32_e64 s[34:35], v1, v9
	v_lshl_add_u64 v[0:1], v[192:193], 1, s[12:13]
	s_mov_b64 s[12:13], 0x18c00000
	v_readlane_b32 s30, v255, 29
	v_lshl_add_u64 v[36:37], v[0:1], 0, s[12:13]
	v_add_u32_e32 v104, v2, v4
	v_add_u32_e32 v105, v3, v4
	v_add_u32_e32 v106, v10, v11
	s_mov_b32 s15, 0x10000
	s_mov_b32 s33, 0x20000
	s_mov_b32 s3, 0x30000
	s_mov_b32 s10, 0x50000
	s_mov_b32 s28, 0x60000
	s_mov_b32 s29, 0x70000
	v_readlane_b32 s31, v255, 30
	s_and_b32 s13, s22, 7
	s_ashr_i32 vcc_lo, s22, 3
	s_ashr_i32 vcc_hi, vcc_lo, 31
	s_lshl_b64 vcc, vcc, 19
	s_lshl_b32 s13, s13, 9
	s_or_b32 vcc_lo, vcc_lo, s13
	v_lshl_add_u64 v[194:195], v[32:33], 0, vcc
	v_lshl_add_u64 v[196:197], v[34:35], 0, vcc
	global_load_dwordx4 v[128:131], v[194:195], off
	global_load_dwordx4 v[132:135], v[196:197], off
	v_add_co_u32_e32 v198, vcc, s15, v194
	s_nop 1
	v_addc_co_u32_e32 v199, vcc, 0, v195, vcc
	global_load_dwordx4 v[136:139], v[198:199], off
	v_add_co_u32_e32 v200, vcc, s15, v196
	s_nop 1
	v_addc_co_u32_e32 v201, vcc, 0, v197, vcc
	global_load_dwordx4 v[140:143], v[200:201], off
	v_add_co_u32_e32 v198, vcc, s33, v194
	s_nop 1
	v_addc_co_u32_e32 v199, vcc, 0, v195, vcc
	global_load_dwordx4 v[144:147], v[198:199], off
	v_add_co_u32_e32 v200, vcc, s33, v196
	s_nop 1
	v_addc_co_u32_e32 v201, vcc, 0, v197, vcc
	global_load_dwordx4 v[148:151], v[200:201], off
	v_add_co_u32_e32 v198, vcc, s3, v194
	s_nop 1
	v_addc_co_u32_e32 v199, vcc, 0, v195, vcc
	global_load_dwordx4 v[152:155], v[198:199], off
	v_add_co_u32_e32 v200, vcc, s3, v196
	s_nop 1
	v_addc_co_u32_e32 v201, vcc, 0, v197, vcc
	global_load_dwordx4 v[156:159], v[200:201], off
	v_add_co_u32_e32 v198, vcc, s96, v194
	s_nop 1
	v_addc_co_u32_e32 v199, vcc, 0, v195, vcc
	global_load_dwordx4 v[160:163], v[198:199], off
	v_add_co_u32_e32 v200, vcc, s96, v196
	s_nop 1
	v_addc_co_u32_e32 v201, vcc, 0, v197, vcc
	global_load_dwordx4 v[164:167], v[200:201], off
	v_add_co_u32_e32 v198, vcc, s10, v194
	s_nop 1
	v_addc_co_u32_e32 v199, vcc, 0, v195, vcc
	global_load_dwordx4 v[168:171], v[198:199], off
	v_add_co_u32_e32 v200, vcc, s10, v196
	s_nop 1
	v_addc_co_u32_e32 v201, vcc, 0, v197, vcc
	global_load_dwordx4 v[172:175], v[200:201], off
	v_add_co_u32_e32 v198, vcc, s28, v194
	s_nop 1
	v_addc_co_u32_e32 v199, vcc, 0, v195, vcc
	global_load_dwordx4 v[176:179], v[198:199], off
	v_add_co_u32_e32 v200, vcc, s28, v196
	s_nop 1
	v_addc_co_u32_e32 v201, vcc, 0, v197, vcc
	global_load_dwordx4 v[180:183], v[200:201], off
	v_add_co_u32_e32 v198, vcc, s29, v194
	s_nop 1
	v_addc_co_u32_e32 v199, vcc, 0, v195, vcc
	global_load_dwordx4 v[184:187], v[198:199], off
	v_add_co_u32_e32 v200, vcc, s29, v196
	s_nop 1
	v_addc_co_u32_e32 v201, vcc, 0, v197, vcc
	global_load_dwordx4 v[188:191], v[200:201], off
	s_waitcnt vmcnt(0)
; #define GAS __attribute__((address_space(1)))
; #define LAS __attribute__((address_space(3)))
; __device__ __forceinline__ unsigned cvt_pk_bf16(float lo, float hi) { unsigned r; asm volatile("v_cvt_pk_bf16_f32 %0, %1, %2" : "=v"(r) : "v"(lo), "v"(hi)); return r; }
; __device__ __forceinline__ unsigned argw(const Frame& F, int w) { return ((const volatile LAS unsigned*)(F.lds + ARGS_OFF + F.zero))[w]; }
; __device__ __forceinline__ void pmat_phase(const Frame& F, const bf16_t* Q, const bf16_t* K, bf16_t* PB, int half) {
;     ...
;     for (int u = F.vcu; u < nunits; u += F.G) {
;         const int head = u & 7, sc = u >> 3;
;         const float lgf = __uint_as_float(__builtin_amdgcn_readfirstlane(argw(F, AW_LG2 + head))), lgb = __uint_as_float(__builtin_amdgcn_readfirstlane(argw(F, AW_LG2 + 8 + head)));
;         const size_t u0 = (size_t)sc * 128 * 2048 + head * 256; const unsigned lq = (unsigned)(srow * 2048 + scc * 8);
; #pragma unroll
;         for (int ii = 0; ii < 8; ++ii) { const u32x4 qv = *(const GAS u32x4*)(Q + u0 + (size_t)ii * 16 * 2048 + lq), kv = *(const GAS u32x4*)(K + u0 + (size_t)ii * 16 * 2048 + lq);
;             *(LAS u32x4*)(lg + (srow + 16 * ii) * PS + scc * 16) = qv; *(LAS u32x4*)(lg + 128 * PS + (srow + 16 * ii) * PS + scc * 16) = kv; }
;         __syncthreads();
;         bf16x8 Qf[8];
; #pragma unroll
;         for (int ks = 0; ks < 8; ++ks) Qf[ks] = *(const LAS bf16x8*)(bQown + 64 * ks);
;         bf16_t* pout = PB + (size_t)u * 16384; const unsigned lpo = (unsigned)((16 * wv + l15) * 128 + 4 * quad); const int i_abs = 16 * wv + l15;
; #pragma unroll
;         for (int jt = 0; jt < 8; ++jt) { f32x4 st = {0.f, 0.f, 0.f, 0.f};
; #pragma unroll
;             for (int ks = 0; ks < 8; ++ks) { const bf16x8 Kf = *(const LAS bf16x8*)(bK + 16 * jt * PS + 64 * ks); st = __builtin_amdgcn_mfma_f32_16x16x32_bf16(Kf, Qf[ks], st, 0, 0, 0); }
; #pragma unroll
;             for (int r = 0; r < 4; ++r) { const int jj = 16 * jt + 4 * quad + r;
;                 st[r] *= __builtin_amdgcn_exp2f(jj <= i_abs ? lgf * (float)(-jj - 1) : lgb * (float)(jj - 128)); }
;             *(GAS u32x2*)(pout + 16 * jt + lpo) = (u32x2){cvt_pk_bf16(st[0], st[1]), cvt_pk_bf16(st[2], st[3])}; }
.LBB0_915:
	s_and_b32 s13, s22, 7
	v_lshl_add_u32 v0, s13, 2, v103
	ds_read_b32 v1, v0 offset:824
	ds_read_b32 v0, v0 offset:856
	s_waitcnt lgkmcnt(1)
	v_readfirstlane_b32 s23, v1
	s_waitcnt lgkmcnt(0)
	v_readfirstlane_b32 s12, v0
	s_nop 1
	v_mul_f32_e32 v107, s23, v39
	s_add_i32 s22, s22, s16
	s_cmp_lt_i32 s22, s18
	s_cselect_b32 s100, 1, 0
	s_waitcnt vmcnt(23)
	ds_write_b128 v104, v[128:131]
	s_waitcnt vmcnt(22)
	ds_write_b128 v105, v[132:135]
	s_waitcnt vmcnt(21)
	ds_write_b128 v104, v[136:139] offset:8448
	s_waitcnt vmcnt(20)
	ds_write_b128 v105, v[140:143] offset:8448
	s_waitcnt vmcnt(19)
	ds_write_b128 v104, v[144:147] offset:16896
	s_waitcnt vmcnt(18)
	ds_write_b128 v105, v[148:151] offset:16896
	s_waitcnt vmcnt(17)
	ds_write_b128 v104, v[152:155] offset:25344
	s_waitcnt vmcnt(16)
	ds_write_b128 v105, v[156:159] offset:25344
	s_waitcnt vmcnt(15)
	ds_write_b128 v104, v[160:163] offset:33792
	s_waitcnt vmcnt(14)
	ds_write_b128 v105, v[164:167] offset:33792
	s_waitcnt vmcnt(13)
	ds_write_b128 v104, v[168:171] offset:42240
	s_waitcnt vmcnt(12)
	ds_write_b128 v105, v[172:175] offset:42240
	s_waitcnt vmcnt(11)
	ds_write_b128 v104, v[176:179] offset:50688
	s_waitcnt vmcnt(10)
	ds_write_b128 v105, v[180:183] offset:50688
	s_waitcnt vmcnt(9)
	ds_write_b128 v104, v[184:187] offset:59136
	s_waitcnt vmcnt(8)
	ds_write_b128 v105, v[188:191] offset:59136
	s_waitcnt lgkmcnt(0)
	s_barrier
	s_cmp_eq_u32 s100, 0
	s_cbranch_scc1 .Lpmat_nopf
	s_and_b32 s13, s22, 7
	s_ashr_i32 vcc_lo, s22, 3
	s_ashr_i32 vcc_hi, vcc_lo, 31
	s_lshl_b64 vcc, vcc, 19
	s_lshl_b32 s13, s13, 9
	s_or_b32 vcc_lo, vcc_lo, s13
	v_lshl_add_u64 v[194:195], v[32:33], 0, vcc
	v_lshl_add_u64 v[196:197], v[34:35], 0, vcc
	global_load_dwordx4 v[128:131], v[194:195], off
	global_load_dwordx4 v[132:135], v[196:197], off
	v_add_co_u32_e32 v198, vcc, s15, v194
	s_nop 1
	v_addc_co_u32_e32 v199, vcc, 0, v195, vcc
	global_load_dwordx4 v[136:139], v[198:199], off
	v_add_co_u32_e32 v200, vcc, s15, v196
	s_nop 1
	v_addc_co_u32_e32 v201, vcc, 0, v197, vcc
	global_load_dwordx4 v[140:143], v[200:201], off
	v_add_co_u32_e32 v198, vcc, s33, v194
	s_nop 1
	v_addc_co_u32_e32 v199, vcc, 0, v195, vcc
	global_load_dwordx4 v[144:147], v[198:199], off
	v_add_co_u32_e32 v200, vcc, s33, v196
	s_nop 1
	v_addc_co_u32_e32 v201, vcc, 0, v197, vcc
	global_load_dwordx4 v[148:151], v[200:201], off
	v_add_co_u32_e32 v198, vcc, s3, v194
	s_nop 1
	v_addc_co_u32_e32 v199, vcc, 0, v195, vcc
	global_load_dwordx4 v[152:155], v[198:199], off
	v_add_co_u32_e32 v200, vcc, s3, v196
	s_nop 1
	v_addc_co_u32_e32 v201, vcc, 0, v197, vcc
	global_load_dwordx4 v[156:159], v[200:201], off
	v_add_co_u32_e32 v198, vcc, s96, v194
	s_nop 1
	v_addc_co_u32_e32 v199, vcc, 0, v195, vcc
	global_load_dwordx4 v[160:163], v[198:199], off
	v_add_co_u32_e32 v200, vcc, s96, v196
	s_nop 1
	v_addc_co_u32_e32 v201, vcc, 0, v197, vcc
	global_load_dwordx4 v[164:167], v[200:201], off
	v_add_co_u32_e32 v198, vcc, s10, v194
	s_nop 1
	v_addc_co_u32_e32 v199, vcc, 0, v195, vcc
	global_load_dwordx4 v[168:171], v[198:199], off
	v_add_co_u32_e32 v200, vcc, s10, v196
	s_nop 1
	v_addc_co_u32_e32 v201, vcc, 0, v197, vcc
	global_load_dwordx4 v[172:175], v[200:201], off
	v_add_co_u32_e32 v198, vcc, s28, v194
	s_nop 1
	v_addc_co_u32_e32 v199, vcc, 0, v195, vcc
	global_load_dwordx4 v[176:179], v[198:199], off
	v_add_co_u32_e32 v200, vcc, s28, v196
	s_nop 1
	v_addc_co_u32_e32 v201, vcc, 0, v197, vcc
	global_load_dwordx4 v[180:183], v[200:201], off
	v_add_co_u32_e32 v198, vcc, s29, v194
	s_nop 1
	v_addc_co_u32_e32 v199, vcc, 0, v195, vcc
	global_load_dwordx4 v[184:187], v[198:199], off
	v_add_co_u32_e32 v200, vcc, s29, v196
	s_nop 1
	v_addc_co_u32_e32 v201, vcc, 0, v197, vcc
	global_load_dwordx4 v[188:191], v[200:201], off
.Lpmat_nopf:
	ds_read_b128 v[28:31], v106
	ds_read_b128 v[24:27], v106 offset:64
	ds_read_b128 v[20:23], v106 offset:128
	ds_read_b128 v[16:19], v106 offset:192
	ds_read_b128 v[12:15], v106 offset:256
	ds_read_b128 v[8:11], v106 offset:320
	ds_read_b128 v[4:7], v106 offset:384
	ds_read_b128 v[0:3], v106 offset:448
	ds_read_b128 v[108:111], v38
	ds_read_b128 v[112:115], v38 offset:64
	ds_read_b128 v[116:119], v38 offset:128
	ds_read_b128 v[120:123], v38 offset:192
	ds_read_b128 v[124:127], v38 offset:256
	s_waitcnt lgkmcnt(4)
	v_mfma_f32_16x16x32_bf16 v[108:111], v[108:111], v[28:31], 0
	s_waitcnt lgkmcnt(3)
	v_mfma_f32_16x16x32_bf16 v[108:111], v[112:115], v[24:27], v[108:111]
	ds_read_b128 v[112:115], v38 offset:320
	s_waitcnt lgkmcnt(3)
	v_mfma_f32_16x16x32_bf16 v[108:111], v[116:119], v[20:23], v[108:111]
	ds_read_b128 v[116:119], v38 offset:384
	s_waitcnt lgkmcnt(3)
	v_mfma_f32_16x16x32_bf16 v[108:111], v[120:123], v[16:19], v[108:111]
	ds_read_b128 v[120:123], v38 offset:448
	s_waitcnt lgkmcnt(3)
	v_mfma_f32_16x16x32_bf16 v[108:111], v[124:127], v[12:15], v[108:111]
	s_waitcnt lgkmcnt(2)
	v_mfma_f32_16x16x32_bf16 v[108:111], v[112:115], v[8:11], v[108:111]
	s_waitcnt lgkmcnt(1)
	v_mfma_f32_16x16x32_bf16 v[108:111], v[116:119], v[4:7], v[108:111]
	s_waitcnt lgkmcnt(0)
	v_mfma_f32_16x16x32_bf16 v[108:111], v[120:123], v[0:3], v[108:111]
	v_mul_f32_e32 v112, s12, v40
	v_cndmask_b32_e64 v107, v107, v112, s[0:1]
	v_exp_f32_e32 v107, v107
	v_mul_f32_e32 v112, s12, v41
	s_nop 3
	v_mul_f32_e32 v107, v107, v108
	v_mul_f32_e32 v108, s23, v42
	v_cndmask_b32_e64 v108, v112, v108, s[34:35]
	v_exp_f32_e32 v108, v108
	v_mul_f32_e32 v112, s12, v44
	v_mul_f32_e32 v108, v108, v109
	v_mul_f32_e32 v109, s23, v43
	v_cndmask_b32_e64 v109, v109, v112, s[36:37]
	v_exp_f32_e32 v109, v109
	v_mul_f32_e32 v112, s12, v46
	v_cvt_pk_bf16_f32 v108, v107, v108
	v_mul_f32_e32 v107, s23, v47
	v_mul_f32_e32 v109, v109, v110
	v_mul_f32_e32 v110, s23, v45
	v_cndmask_b32_e64 v110, v110, v112, s[38:39]
	v_exp_f32_e32 v110, v110
	s_nop 0
	v_mul_f32_e32 v110, v110, v111
	v_cvt_pk_bf16_f32 v109, v109, v110
	global_store_dwordx2 v[36:37], v[108:109], off
	ds_read_b128 v[108:111], v38 offset:8448
	ds_read_b128 v[112:115], v38 offset:8512
	ds_read_b128 v[116:119], v38 offset:8576
	ds_read_b128 v[120:123], v38 offset:8640
	ds_read_b128 v[124:127], v38 offset:8704
	s_waitcnt lgkmcnt(4)
; #define GAS __attribute__((address_space(1)))
; #define LAS __attribute__((address_space(3)))
; __device__ __forceinline__ unsigned cvt_pk_bf16(float lo, float hi) { unsigned r; asm volatile("v_cvt_pk_bf16_f32 %0, %1, %2" : "=v"(r) : "v"(lo), "v"(hi)); return r; }
; __device__ __forceinline__ void pmat_phase(const Frame& F, const bf16_t* Q, const bf16_t* K, bf16_t* PB, int half) {
;     ...
; #pragma unroll
;         for (int jt = 0; jt < 8; ++jt) { f32x4 st = {0.f, 0.f, 0.f, 0.f};
; #pragma unroll
;             for (int ks = 0; ks < 8; ++ks) { const bf16x8 Kf = *(const LAS bf16x8*)(bK + 16 * jt * PS + 64 * ks); st = __builtin_amdgcn_mfma_f32_16x16x32_bf16(Kf, Qf[ks], st, 0, 0, 0); }
; #pragma unroll
;             for (int r = 0; r < 4; ++r) { const int jj = 16 * jt + 4 * quad + r;
;                 st[r] *= __builtin_amdgcn_exp2f(jj <= i_abs ? lgf * (float)(-jj - 1) : lgb * (float)(jj - 128)); }
;             *(GAS u32x2*)(pout + 16 * jt + lpo) = (u32x2){cvt_pk_bf16(st[0], st[1]), cvt_pk_bf16(st[2], st[3])}; }
	v_mfma_f32_16x16x32_bf16 v[108:111], v[108:111], v[28:31], 0
	s_waitcnt lgkmcnt(3)
	v_mfma_f32_16x16x32_bf16 v[108:111], v[112:115], v[24:27], v[108:111]
	ds_read_b128 v[112:115], v38 offset:8768
	s_waitcnt lgkmcnt(3)
	v_mfma_f32_16x16x32_bf16 v[108:111], v[116:119], v[20:23], v[108:111]
	ds_read_b128 v[116:119], v38 offset:8832
	s_waitcnt lgkmcnt(3)
	v_mfma_f32_16x16x32_bf16 v[108:111], v[120:123], v[16:19], v[108:111]
	ds_read_b128 v[120:123], v38 offset:8896
	s_waitcnt lgkmcnt(3)
	v_mfma_f32_16x16x32_bf16 v[108:111], v[124:127], v[12:15], v[108:111]
	s_waitcnt lgkmcnt(2)
	v_mfma_f32_16x16x32_bf16 v[108:111], v[112:115], v[8:11], v[108:111]
	s_waitcnt lgkmcnt(1)
	v_mfma_f32_16x16x32_bf16 v[108:111], v[116:119], v[4:7], v[108:111]
	s_waitcnt lgkmcnt(0)
	v_mfma_f32_16x16x32_bf16 v[108:111], v[120:123], v[0:3], v[108:111]
	v_mul_f32_e32 v112, s12, v48
	v_cndmask_b32_e64 v107, v107, v112, s[40:41]
	v_exp_f32_e32 v107, v107
	v_mul_f32_e32 v112, s12, v50
	s_nop 3
	v_mul_f32_e32 v107, v107, v108
	v_mul_f32_e32 v108, s23, v49
	v_cndmask_b32_e64 v108, v108, v112, s[42:43]
	v_exp_f32_e32 v108, v108
	v_mul_f32_e32 v112, s12, v52
	v_mul_f32_e32 v108, v108, v109
	v_mul_f32_e32 v109, s23, v51
	v_cndmask_b32_e64 v109, v109, v112, s[44:45]
	v_exp_f32_e32 v109, v109
	v_mul_f32_e32 v112, s12, v54
	v_cvt_pk_bf16_f32 v108, v107, v108
	v_mul_f32_e32 v107, s23, v55
	v_mul_f32_e32 v109, v109, v110
	v_mul_f32_e32 v110, s23, v53
	v_cndmask_b32_e64 v110, v110, v112, s[46:47]
	v_exp_f32_e32 v110, v110
	s_nop 0
	v_mul_f32_e32 v110, v110, v111
	v_cvt_pk_bf16_f32 v109, v109, v110
	global_store_dwordx2 v[36:37], v[108:109], off offset:32
	ds_read_b128 v[108:111], v38 offset:16896
	ds_read_b128 v[112:115], v38 offset:16960
	ds_read_b128 v[116:119], v38 offset:17024
	ds_read_b128 v[120:123], v38 offset:17088
	ds_read_b128 v[124:127], v38 offset:17152
	s_waitcnt lgkmcnt(4)
	v_mfma_f32_16x16x32_bf16 v[108:111], v[108:111], v[28:31], 0
	s_waitcnt lgkmcnt(3)
	v_mfma_f32_16x16x32_bf16 v[108:111], v[112:115], v[24:27], v[108:111]
	ds_read_b128 v[112:115], v38 offset:17216
	s_waitcnt lgkmcnt(3)
	v_mfma_f32_16x16x32_bf16 v[108:111], v[116:119], v[20:23], v[108:111]
	ds_read_b128 v[116:119], v38 offset:17280
	s_waitcnt lgkmcnt(3)
	v_mfma_f32_16x16x32_bf16 v[108:111], v[120:123], v[16:19], v[108:111]
	ds_read_b128 v[120:123], v38 offset:17344
	s_waitcnt lgkmcnt(3)
	v_mfma_f32_16x16x32_bf16 v[108:111], v[124:127], v[12:15], v[108:111]
	s_waitcnt lgkmcnt(2)
	v_mfma_f32_16x16x32_bf16 v[108:111], v[112:115], v[8:11], v[108:111]
	s_waitcnt lgkmcnt(1)
	v_mfma_f32_16x16x32_bf16 v[108:111], v[116:119], v[4:7], v[108:111]
	s_waitcnt lgkmcnt(0)
	v_mfma_f32_16x16x32_bf16 v[108:111], v[120:123], v[0:3], v[108:111]
	v_mul_f32_e32 v112, s12, v56
	v_cndmask_b32_e64 v107, v107, v112, s[48:49]
	v_exp_f32_e32 v107, v107
	v_mul_f32_e32 v112, s12, v58
	s_nop 3
	v_mul_f32_e32 v107, v107, v108
	v_mul_f32_e32 v108, s23, v57
	v_cndmask_b32_e64 v108, v108, v112, s[50:51]
	v_exp_f32_e32 v108, v108
	v_mul_f32_e32 v112, s12, v60
	v_mul_f32_e32 v108, v108, v109
	v_mul_f32_e32 v109, s23, v59
	v_cndmask_b32_e64 v109, v109, v112, s[52:53]
	v_exp_f32_e32 v109, v109
	v_mul_f32_e32 v112, s12, v62
	v_cvt_pk_bf16_f32 v108, v107, v108
	v_mul_f32_e32 v107, s23, v63
	v_mul_f32_e32 v109, v109, v110
	v_mul_f32_e32 v110, s23, v61
	v_cndmask_b32_e64 v110, v110, v112, s[54:55]
	v_exp_f32_e32 v110, v110
	s_nop 0
	v_mul_f32_e32 v110, v110, v111
	v_cvt_pk_bf16_f32 v109, v109, v110
	global_store_dwordx2 v[36:37], v[108:109], off offset:64
	ds_read_b128 v[108:111], v38 offset:25344
	ds_read_b128 v[112:115], v38 offset:25408
	ds_read_b128 v[116:119], v38 offset:25472
	ds_read_b128 v[120:123], v38 offset:25536
	ds_read_b128 v[124:127], v38 offset:25600
	s_waitcnt lgkmcnt(4)
	v_mfma_f32_16x16x32_bf16 v[108:111], v[108:111], v[28:31], 0
	s_waitcnt lgkmcnt(3)
	v_mfma_f32_16x16x32_bf16 v[108:111], v[112:115], v[24:27], v[108:111]
	ds_read_b128 v[112:115], v38 offset:25664
	s_waitcnt lgkmcnt(3)
	v_mfma_f32_16x16x32_bf16 v[108:111], v[116:119], v[20:23], v[108:111]
	ds_read_b128 v[116:119], v38 offset:25728
	s_waitcnt lgkmcnt(3)
	v_mfma_f32_16x16x32_bf16 v[108:111], v[120:123], v[16:19], v[108:111]
	ds_read_b128 v[120:123], v38 offset:25792
	s_waitcnt lgkmcnt(3)
	v_mfma_f32_16x16x32_bf16 v[108:111], v[124:127], v[12:15], v[108:111]
	s_waitcnt lgkmcnt(2)
	v_mfma_f32_16x16x32_bf16 v[108:111], v[112:115], v[8:11], v[108:111]
	s_waitcnt lgkmcnt(1)
	v_mfma_f32_16x16x32_bf16 v[108:111], v[116:119], v[4:7], v[108:111]
	s_waitcnt lgkmcnt(0)
	v_mfma_f32_16x16x32_bf16 v[108:111], v[120:123], v[0:3], v[108:111]
	v_mul_f32_e32 v112, s12, v64
	v_cndmask_b32_e64 v107, v107, v112, s[56:57]
	v_exp_f32_e32 v107, v107
	v_mul_f32_e32 v112, s12, v66
	s_nop 3
	v_mul_f32_e32 v107, v107, v108
	v_mul_f32_e32 v108, s23, v65
	v_cndmask_b32_e64 v108, v108, v112, s[58:59]
	v_exp_f32_e32 v108, v108
	v_mul_f32_e32 v112, s12, v68
	v_mul_f32_e32 v108, v108, v109
	v_mul_f32_e32 v109, s23, v67
	v_cndmask_b32_e64 v109, v109, v112, s[60:61]
	v_exp_f32_e32 v109, v109
	v_mul_f32_e32 v112, s12, v70
	v_cvt_pk_bf16_f32 v108, v107, v108
	v_mul_f32_e32 v107, s23, v71
	v_mul_f32_e32 v109, v109, v110
	v_mul_f32_e32 v110, s23, v69
	v_cndmask_b32_e64 v110, v110, v112, s[62:63]
	v_exp_f32_e32 v110, v110
	s_nop 0
	v_mul_f32_e32 v110, v110, v111
	v_cvt_pk_bf16_f32 v109, v109, v110
	global_store_dwordx2 v[36:37], v[108:109], off offset:96
	ds_read_b128 v[108:111], v38 offset:33792
	ds_read_b128 v[112:115], v38 offset:33856
	ds_read_b128 v[116:119], v38 offset:33920
	ds_read_b128 v[120:123], v38 offset:33984
	ds_read_b128 v[124:127], v38 offset:34048
	s_waitcnt lgkmcnt(4)
; #define GAS __attribute__((address_space(1)))
; #define LAS __attribute__((address_space(3)))
; __device__ __forceinline__ unsigned cvt_pk_bf16(float lo, float hi) { unsigned r; asm volatile("v_cvt_pk_bf16_f32 %0, %1, %2" : "=v"(r) : "v"(lo), "v"(hi)); return r; }
; __device__ __forceinline__ void pmat_phase(const Frame& F, const bf16_t* Q, const bf16_t* K, bf16_t* PB, int half) {
;     ...
; #pragma unroll
;         for (int jt = 0; jt < 8; ++jt) { f32x4 st = {0.f, 0.f, 0.f, 0.f};
; #pragma unroll
;             for (int ks = 0; ks < 8; ++ks) { const bf16x8 Kf = *(const LAS bf16x8*)(bK + 16 * jt * PS + 64 * ks); st = __builtin_amdgcn_mfma_f32_16x16x32_bf16(Kf, Qf[ks], st, 0, 0, 0); }
; #pragma unroll
;             for (int r = 0; r < 4; ++r) { const int jj = 16 * jt + 4 * quad + r;
;                 st[r] *= __builtin_amdgcn_exp2f(jj <= i_abs ? lgf * (float)(-jj - 1) : lgb * (float)(jj - 128)); }
;             *(GAS u32x2*)(pout + 16 * jt + lpo) = (u32x2){cvt_pk_bf16(st[0], st[1]), cvt_pk_bf16(st[2], st[3])}; }
	v_mfma_f32_16x16x32_bf16 v[108:111], v[108:111], v[28:31], 0
	s_waitcnt lgkmcnt(3)
	v_mfma_f32_16x16x32_bf16 v[108:111], v[112:115], v[24:27], v[108:111]
	ds_read_b128 v[112:115], v38 offset:34112
	s_waitcnt lgkmcnt(3)
	v_mfma_f32_16x16x32_bf16 v[108:111], v[116:119], v[20:23], v[108:111]
	ds_read_b128 v[116:119], v38 offset:34176
	s_waitcnt lgkmcnt(3)
	v_mfma_f32_16x16x32_bf16 v[108:111], v[120:123], v[16:19], v[108:111]
	ds_read_b128 v[120:123], v38 offset:34240
	s_waitcnt lgkmcnt(3)
	v_mfma_f32_16x16x32_bf16 v[108:111], v[124:127], v[12:15], v[108:111]
	s_waitcnt lgkmcnt(2)
	v_mfma_f32_16x16x32_bf16 v[108:111], v[112:115], v[8:11], v[108:111]
	s_waitcnt lgkmcnt(1)
	v_mfma_f32_16x16x32_bf16 v[108:111], v[116:119], v[4:7], v[108:111]
	s_waitcnt lgkmcnt(0)
	v_mfma_f32_16x16x32_bf16 v[108:111], v[120:123], v[0:3], v[108:111]
	v_mul_f32_e32 v112, s12, v72
	v_cndmask_b32_e64 v107, v107, v112, s[64:65]
	v_exp_f32_e32 v107, v107
	v_mul_f32_e32 v112, s12, v74
	s_nop 3
	v_mul_f32_e32 v107, v107, v108
	v_mul_f32_e32 v108, s23, v73
	v_cndmask_b32_e64 v108, v108, v112, s[66:67]
	v_exp_f32_e32 v108, v108
	v_mul_f32_e32 v112, s12, v76
	v_mul_f32_e32 v108, v108, v109
	v_mul_f32_e32 v109, s23, v75
	v_cndmask_b32_e64 v109, v109, v112, s[68:69]
	v_exp_f32_e32 v109, v109
	v_mul_f32_e32 v112, s12, v78
	v_cvt_pk_bf16_f32 v108, v107, v108
	v_mul_f32_e32 v107, s23, v79
	v_mul_f32_e32 v109, v109, v110
	v_mul_f32_e32 v110, s23, v77
	v_cndmask_b32_e64 v110, v110, v112, s[70:71]
	v_exp_f32_e32 v110, v110
	s_nop 0
	v_mul_f32_e32 v110, v110, v111
	v_cvt_pk_bf16_f32 v109, v109, v110
	global_store_dwordx2 v[36:37], v[108:109], off offset:128
	ds_read_b128 v[108:111], v38 offset:42240
	ds_read_b128 v[112:115], v38 offset:42304
	ds_read_b128 v[116:119], v38 offset:42368
	ds_read_b128 v[120:123], v38 offset:42432
	ds_read_b128 v[124:127], v38 offset:42496
	s_waitcnt lgkmcnt(4)
	v_mfma_f32_16x16x32_bf16 v[108:111], v[108:111], v[28:31], 0
	s_waitcnt lgkmcnt(3)
	v_mfma_f32_16x16x32_bf16 v[108:111], v[112:115], v[24:27], v[108:111]
	ds_read_b128 v[112:115], v38 offset:42560
	s_waitcnt lgkmcnt(3)
	v_mfma_f32_16x16x32_bf16 v[108:111], v[116:119], v[20:23], v[108:111]
	ds_read_b128 v[116:119], v38 offset:42624
	s_waitcnt lgkmcnt(3)
	v_mfma_f32_16x16x32_bf16 v[108:111], v[120:123], v[16:19], v[108:111]
	ds_read_b128 v[120:123], v38 offset:42688
	s_waitcnt lgkmcnt(3)
	v_mfma_f32_16x16x32_bf16 v[108:111], v[124:127], v[12:15], v[108:111]
	s_waitcnt lgkmcnt(2)
	v_mfma_f32_16x16x32_bf16 v[108:111], v[112:115], v[8:11], v[108:111]
	s_waitcnt lgkmcnt(1)
	v_mfma_f32_16x16x32_bf16 v[108:111], v[116:119], v[4:7], v[108:111]
	s_waitcnt lgkmcnt(0)
	v_mfma_f32_16x16x32_bf16 v[108:111], v[120:123], v[0:3], v[108:111]
	v_mul_f32_e32 v112, s12, v80
	v_cndmask_b32_e64 v107, v107, v112, s[72:73]
	v_exp_f32_e32 v107, v107
	v_mul_f32_e32 v112, s12, v82
	s_nop 3
	v_mul_f32_e32 v107, v107, v108
	v_mul_f32_e32 v108, s23, v81
	v_cndmask_b32_e64 v108, v108, v112, s[74:75]
	v_exp_f32_e32 v108, v108
	v_mul_f32_e32 v112, s12, v84
	v_mul_f32_e32 v108, v108, v109
	v_mul_f32_e32 v109, s23, v83
	v_cndmask_b32_e64 v109, v109, v112, s[76:77]
	v_exp_f32_e32 v109, v109
	v_mul_f32_e32 v112, s12, v86
	v_cvt_pk_bf16_f32 v108, v107, v108
	v_mul_f32_e32 v107, s23, v87
	v_mul_f32_e32 v109, v109, v110
	v_mul_f32_e32 v110, s23, v85
	v_cndmask_b32_e64 v110, v110, v112, s[78:79]
	v_exp_f32_e32 v110, v110
	s_nop 0
	v_mul_f32_e32 v110, v110, v111
	v_cvt_pk_bf16_f32 v109, v109, v110
	global_store_dwordx2 v[36:37], v[108:109], off offset:160
	ds_read_b128 v[108:111], v38 offset:50688
	ds_read_b128 v[112:115], v38 offset:50752
	ds_read_b128 v[116:119], v38 offset:50816
	ds_read_b128 v[120:123], v38 offset:50880
	ds_read_b128 v[124:127], v38 offset:50944
	s_waitcnt lgkmcnt(4)
; #define GAS __attribute__((address_space(1)))
; #define LAS __attribute__((address_space(3)))
; __device__ __forceinline__ unsigned cvt_pk_bf16(float lo, float hi) { unsigned r; asm volatile("v_cvt_pk_bf16_f32 %0, %1, %2" : "=v"(r) : "v"(lo), "v"(hi)); return r; }
; __device__ __forceinline__ void pmat_phase(const Frame& F, const bf16_t* Q, const bf16_t* K, bf16_t* PB, int half) {
;     ...
; #pragma unroll
;         for (int jt = 0; jt < 8; ++jt) { f32x4 st = {0.f, 0.f, 0.f, 0.f};
; #pragma unroll
;             for (int ks = 0; ks < 8; ++ks) { const bf16x8 Kf = *(const LAS bf16x8*)(bK + 16 * jt * PS + 64 * ks); st = __builtin_amdgcn_mfma_f32_16x16x32_bf16(Kf, Qf[ks], st, 0, 0, 0); }
; #pragma unroll
;             for (int r = 0; r < 4; ++r) { const int jj = 16 * jt + 4 * quad + r;
;                 st[r] *= __builtin_amdgcn_exp2f(jj <= i_abs ? lgf * (float)(-jj - 1) : lgb * (float)(jj - 128)); }
;             *(GAS u32x2*)(pout + 16 * jt + lpo) = (u32x2){cvt_pk_bf16(st[0], st[1]), cvt_pk_bf16(st[2], st[3])}; }
;         __syncthreads();
	v_mfma_f32_16x16x32_bf16 v[108:111], v[108:111], v[28:31], 0
	s_waitcnt lgkmcnt(3)
	v_mfma_f32_16x16x32_bf16 v[108:111], v[112:115], v[24:27], v[108:111]
	ds_read_b128 v[112:115], v38 offset:51008
	s_waitcnt lgkmcnt(3)
	v_mfma_f32_16x16x32_bf16 v[108:111], v[116:119], v[20:23], v[108:111]
	ds_read_b128 v[116:119], v38 offset:51072
	s_waitcnt lgkmcnt(3)
	v_mfma_f32_16x16x32_bf16 v[108:111], v[120:123], v[16:19], v[108:111]
	ds_read_b128 v[120:123], v38 offset:51136
	s_waitcnt lgkmcnt(3)
	v_mfma_f32_16x16x32_bf16 v[108:111], v[124:127], v[12:15], v[108:111]
	s_waitcnt lgkmcnt(2)
	v_mfma_f32_16x16x32_bf16 v[108:111], v[112:115], v[8:11], v[108:111]
	s_waitcnt lgkmcnt(1)
	v_mfma_f32_16x16x32_bf16 v[108:111], v[116:119], v[4:7], v[108:111]
	s_waitcnt lgkmcnt(0)
	v_mfma_f32_16x16x32_bf16 v[108:111], v[120:123], v[0:3], v[108:111]
	v_mul_f32_e32 v112, s12, v88
	v_cndmask_b32_e64 v107, v107, v112, s[80:81]
	v_exp_f32_e32 v107, v107
	v_mul_f32_e32 v112, s12, v90
	s_nop 3
	v_mul_f32_e32 v107, v107, v108
	v_mul_f32_e32 v108, s23, v89
	v_cndmask_b32_e64 v108, v108, v112, s[82:83]
	v_exp_f32_e32 v108, v108
	v_mul_f32_e32 v112, s12, v92
	v_mul_f32_e32 v108, v108, v109
	v_mul_f32_e32 v109, s23, v91
	v_cndmask_b32_e64 v109, v109, v112, s[84:85]
	v_exp_f32_e32 v109, v109
	v_mul_f32_e32 v112, s12, v94
	v_cvt_pk_bf16_f32 v108, v107, v108
	v_mul_f32_e32 v109, v109, v110
	v_mul_f32_e32 v110, s23, v93
	v_cndmask_b32_e64 v110, v110, v112, s[86:87]
	v_exp_f32_e32 v110, v110
	s_nop 0
	v_mul_f32_e32 v110, v110, v111
	v_cvt_pk_bf16_f32 v109, v109, v110
	global_store_dwordx2 v[36:37], v[108:109], off offset:192
	ds_read_b128 v[108:111], v38 offset:59136
	s_waitcnt lgkmcnt(0)
	v_mfma_f32_16x16x32_bf16 v[28:31], v[108:111], v[28:31], 0
	ds_read_b128 v[108:111], v38 offset:59200
	s_waitcnt lgkmcnt(0)
	v_mfma_f32_16x16x32_bf16 v[24:27], v[108:111], v[24:27], v[28:31]
	s_nop 4
	ds_read_b128 v[28:31], v38 offset:59264
	s_waitcnt lgkmcnt(0)
	v_mfma_f32_16x16x32_bf16 v[20:23], v[28:31], v[20:23], v[24:27]
	s_nop 2
	ds_read_b128 v[24:27], v38 offset:59328
	s_waitcnt lgkmcnt(0)
	v_mfma_f32_16x16x32_bf16 v[16:19], v[24:27], v[16:19], v[20:23]
	s_nop 2
	ds_read_b128 v[20:23], v38 offset:59392
	s_waitcnt lgkmcnt(0)
	v_mfma_f32_16x16x32_bf16 v[12:15], v[20:23], v[12:15], v[16:19]
	s_nop 2
	ds_read_b128 v[16:19], v38 offset:59456
	s_waitcnt lgkmcnt(0)
	v_mfma_f32_16x16x32_bf16 v[8:11], v[16:19], v[8:11], v[12:15]
	s_nop 2
	ds_read_b128 v[12:15], v38 offset:59520
	s_waitcnt lgkmcnt(0)
	v_mfma_f32_16x16x32_bf16 v[4:7], v[12:15], v[4:7], v[8:11]
	s_nop 2
	ds_read_b128 v[8:11], v38 offset:59584
	s_waitcnt lgkmcnt(0)
	v_mfma_f32_16x16x32_bf16 v[0:3], v[8:11], v[0:3], v[4:7]
	s_nop 2
	v_mul_f32_e32 v4, s23, v95
	v_mul_f32_e32 v5, s12, v96
	v_cndmask_b32_e64 v4, v4, v5, s[88:89]
	v_exp_f32_e32 v4, v4
	v_mul_f32_e32 v5, s12, v98
	v_mul_f32_e32 v0, v4, v0
	v_mul_f32_e32 v4, s23, v97
	v_cndmask_b32_e64 v4, v4, v5, s[90:91]
	v_exp_f32_e32 v4, v4
	v_mul_f32_e32 v5, s12, v100
	v_mul_f32_e32 v1, v4, v1
	v_mul_f32_e32 v4, s23, v99
	v_cndmask_b32_e64 v4, v4, v5, s[92:93]
	v_exp_f32_e32 v4, v4
	v_mul_f32_e32 v5, s12, v102
	v_cvt_pk_bf16_f32 v0, v0, v1
	v_mul_f32_e32 v2, v4, v2
	v_mul_f32_e32 v4, s23, v101
	v_cndmask_b32_e64 v4, v4, v5, s[94:95]
	v_exp_f32_e32 v4, v4
	s_nop 0
	v_mul_f32_e32 v3, v4, v3
	v_cvt_pk_bf16_f32 v1, v2, v3
	global_store_dwordx2 v[36:37], v[0:1], off offset:224
	v_lshl_add_u64 v[36:37], v[36:37], 0, s[30:31]
	s_barrier
	s_cmp_lg_u32 s100, 0
	s_cbranch_scc1 .LBB0_915
	v_readlane_b32 s94, v255, 49
	s_mov_b32 s93, 0x10000
	v_readlane_b32 s95, v255, 50
